# GLA items remapped over blocks (one (batch, head) per XCD; the dv halves / mirrored directions that read the same q,k,v rows share an L2)
# speedup vs baseline: 1.1288x; 1.0066x over previous
.LBB0_175:
	s_cmp_gt_i32 s54, 2
	s_cselect_b64 s[6:7], -1, 0
	s_cmp_lt_i32 s55, 3
	s_cselect_b64 s[8:9], -1, 0
	s_or_b64 s[6:7], s[6:7], s[8:9]
	s_and_b64 vcc, exec, s[6:7]
	s_cbranch_vccnz .LBB0_258
	s_cmpk_gt_i32 s2, 0x9ff
	s_cbranch_scc1 .LBB0_204
	s_load_dwordx8 s[12:19], s[0:1], 0xd8
	s_load_dwordx2 s[6:7], s[0:1], 0xa0
	s_load_dwordx4 s[8:11], s[0:1], 0x18
	v_lshlrev_b32_e32 v0, 3, v168
	v_lshrrev_b32_e32 v1, 7, v168
	v_and_b32_e32 v72, 0x3f8, v0
	v_mov_b32_e32 v75, 0
	v_and_b32_e32 v0, 63, v168
	v_or_b32_e32 v73, 0xfffff000, v1
	v_lshlrev_b32_e32 v84, 1, v0
	v_mov_b32_e32 v85, v75
	v_lshlrev_b32_e32 v1, 3, v0
	s_waitcnt lgkmcnt(0)
	v_lshl_add_u64 v[86:87], s[18:19], 0, v[84:85]
	v_add_u32_e32 v85, 16, v1
	s_movk_i32 s3, 0x118
	s_load_dwordx4 s[20:23], s[0:1], 0x100
	s_load_dwordx2 s[18:19], s[0:1], 0x118
	s_add_u32 s24, s6, 0x2000000
	v_lshlrev_b32_e32 v74, 2, v72
	v_and_b32_e32 v136, 15, v168
	v_mad_u32_u24 v137, v0, s3, v85
	s_movk_i32 s3, 0xff70
	s_addc_u32 s25, s7, 0
	v_lshl_add_u64 v[76:77], s[8:9], 0, v[74:75]
	s_mov_b64 s[6:7], 0x1000
	v_mad_i32_i24 v138, v0, s3, v137
	s_add_i32 s3, 16, 0x13800
	v_mul_u32_u24_e32 v2, 0x48, v136
	v_lshl_add_u64 v[78:79], v[76:77], 0, s[6:7]
	s_mov_b64 s[6:7], 0x2000
	v_lshl_add_u64 v[82:83], s[10:11], 0, v[74:75]
	v_lshlrev_b32_e32 v2, 1, v2
	v_and_b32_e32 v3, 48, v168
	v_add_u32_e32 v141, s3, v1
	v_lshlrev_b32_e32 v1, 5, v168
	v_lshlrev_b32_e32 v74, 2, v0
	v_lshl_add_u64 v[80:81], v[76:77], 0, s[6:7]
	v_lshl_add_u32 v139, v136, 2, s3
	v_add3_u32 v140, 16, v2, v3
	v_and_b32_e32 v142, 0x600, v1
	v_lshl_add_u64 v[88:89], s[16:17], 0, v[74:75]
	s_movk_i32 s3, 0x1fff
	s_movk_i32 s30, 0x7fff
	s_mov_b32 s17, 0
	v_lshlrev_b32_e32 v90, 2, v0
	v_mov_b32_e32 v143, 1
	s_mov_b32 s31, s2
	s_cmp_eq_u32 s52, 0x200
	s_cbranch_scc0 .Lp2_noswz
	s_and_b32 s90, s2, 7
	s_lshr_b32 s91, s2, 3
	s_lshl_b32 s90, s90, 6
	s_or_b32 s31, s90, s91
.Lp2_noswz:
	s_branch .LBB0_179

.LBB0_329:
	s_cmp_gt_i32 s54, 4
	s_cselect_b64 s[6:7], -1, 0
	s_cmp_lt_i32 s55, 5
	s_waitcnt lgkmcnt(0)
	s_cselect_b64 s[8:9], -1, 0
	s_or_b64 s[6:7], s[6:7], s[8:9]
	s_and_b64 vcc, exec, s[6:7]
	s_cbranch_vccnz .LBB0_391
	s_cmpk_gt_i32 s2, 0x1ff
	s_cbranch_scc1 .LBB0_337
	s_load_dwordx4 s[8:11], s[0:1], 0xe8
	s_load_dwordx4 s[48:51], s[0:1], 0x100
	v_and_b32_e32 v0, 63, v168
	v_lshrrev_b32_e32 v1, 2, v168
	v_mov_b32_e32 v75, 0
	v_and_b32_e32 v73, 12, v1
	v_lshlrev_b32_e32 v74, 1, v0
	v_lshlrev_b32_e32 v1, 3, v0
	s_waitcnt lgkmcnt(0)
	v_lshl_add_u64 v[76:77], s[10:11], 0, v[74:75]
	v_add_u32_e32 v124, 16, v1
	v_lshlrev_b32_e32 v74, 2, v0
	v_and_b32_e32 v72, 15, v168
	v_sub_u32_e32 v125, v124, v74
	s_movk_i32 s3, 0x11c
	v_mad_u32_u24 v126, v0, s3, v125
	v_lshl_add_u32 v127, v72, 1, 16
	s_movk_i32 s3, 0xff70
	v_mul_u32_u24_e32 v2, 0x8e, v72
	v_and_b32_e32 v3, 48, v168
	v_mad_i32_i24 v128, v0, s3, v126
	s_add_i32 s3, 16, 0x13800
	v_add3_u32 v130, v127, v2, v3
	v_lshl_add_u32 v129, v72, 2, s3
	v_lshl_add_u32 v131, v72, 7, v130
	v_add_u32_e32 v132, s3, v1
	v_lshl_add_u64 v[78:79], s[8:9], 0, v[74:75]
	s_mov_b32 s57, 0
	v_sub_u32_e32 v133, 0, v73
	s_movk_i32 s3, 0xd8
	s_movk_i32 s60, 0x2000
	v_lshlrev_b32_e32 v80, 2, v0
	v_mov_b32_e32 v81, v75
	v_lshlrev_b32_e32 v82, 1, v72
	v_mov_b32_e32 v83, v75
	s_movk_i32 s61, 0x90
	s_movk_i32 s62, 0x110
	s_mov_b32 s63, 0xffff0000
	s_movk_i32 s64, 0x7fff
	s_mov_b32 s65, s2
	s_cmp_eq_u32 s52, 0x200
	s_cbranch_scc0 .Lp4_noswz
	s_and_b32 s90, s2, 7
	s_lshr_b32 s91, s2, 3
	s_lshl_b32 s90, s90, 6
	s_or_b32 s65, s90, s91
